# v15 + streaming (nt) hint on the final-norm prompt-row output stores, so less dirty output sits in L2 when the tail-tile workgroups publish
# speedup vs baseline: 1.0005x; 1.0005x over previous
; __device__ __forceinline__ float bflo(unsigned w) { return __uint_as_float(w << 16); }
; __device__ __forceinline__ float bfhi(unsigned w) { return __uint_as_float(w & 0xffff0000u); }
; __device__ __forceinline__ void phase8(const Params& p) {
;     ...
;     for (long it = gtid; it < total; it += gsz) {
;         const long row = it >> 7; const int c8 = (int)(it & 127) * 8;
;         const float rs = rsqrtf(rsq[row] * (1.f / 1024.f) + EPS);
;         const u32x4 xw = *(const u32x4*)(xb + row * 1024 + c8);
;         const f32x4 g0 = *(const f32x4*)(g + c8), g1 = *(const f32x4*)(g + c8 + 4);
;         f32x4 o0, o1;
;         o0[0] = bflo(xw.x) * rs * g0[0]; o0[1] = bfhi(xw.x) * rs * g0[1]; o0[2] = bflo(xw.y) * rs * g0[2]; o0[3] = bfhi(xw.y) * rs * g0[3];
;         o1[0] = bflo(xw.z) * rs * g1[0]; o1[1] = bfhi(xw.z) * rs * g1[1]; o1[2] = bflo(xw.w) * rs * g1[2]; o1[3] = bfhi(xw.w) * rs * g1[3];
;         *(f32x4*)(y + row * 1024 + c8) = o0; *(f32x4*)(y + row * 1024 + c8 + 4) = o1;
;     }
.Lp8_loop_prompt:
	v_lshrrev_b64 v[18:19], 7, v[0:1]
	v_lshl_add_u64 v[6:7], v[18:19], 2, s[0:1]
	global_load_dword v22, v[6:7], off
	v_and_b32_e32 v5, 0x7f, v0
	v_lshlrev_b32_e32 v5, 3, v5
	v_lshlrev_b64 v[8:9], 11, v[18:19]
	v_lshlrev_b32_e32 v136, 1, v5
	v_lshl_add_u64 v[6:7], s[4:5], 0, v[8:9]
	v_lshl_add_u64 v[20:21], v[6:7], 0, v[136:137]
	v_lshlrev_b32_e32 v136, 2, v5
	global_load_dwordx4 v[6:9], v[20:21], off
	global_load_dwordx4 v[10:13], v136, s[40:41]
	global_load_dwordx4 v[14:17], v136, s[40:41] offset:16
	v_lshl_add_u64 v[0:1], v[0:1], 0, s[6:7]
	v_cmp_lt_u64_e32 vcc, s[10:11], v[0:1]
	s_or_b64 s[8:9], vcc, s[8:9]
	v_lshlrev_b64 v[18:19], 12, v[18:19]
	v_lshl_add_u64 v[18:19], s[42:43], 0, v[18:19]
	v_lshl_add_u64 v[18:19], v[18:19], 0, v[136:137]
	s_waitcnt vmcnt(0)
	v_fmamk_f32 v5, v22, 0x3a800000, v4
	v_mul_f32_e32 v20, 0x4b800000, v5
	v_cmp_gt_f32_e32 vcc, s12, v5
	v_and_b32_e32 v21, 0xffff0000, v6
	s_nop 0
	v_cndmask_b32_e32 v5, v5, v20, vcc
	v_rsq_f32_e32 v5, v5
	v_lshlrev_b32_e32 v20, 16, v6
	v_lshlrev_b32_e32 v6, 16, v7
	v_and_b32_e32 v7, 0xffff0000, v7
	v_mul_f32_e32 v24, 0x45800000, v5
	v_cndmask_b32_e32 v24, v5, v24, vcc
	v_lshlrev_b32_e32 v22, 16, v8
	v_and_b32_e32 v23, 0xffff0000, v8
	v_lshlrev_b32_e32 v8, 16, v9
	v_and_b32_e32 v9, 0xffff0000, v9
	v_pk_mul_f32 v[20:21], v[24:25], v[20:21] op_sel_hi:[0,1]
	v_pk_mul_f32 v[26:27], v[24:25], v[6:7] op_sel_hi:[0,1]
	v_pk_mul_f32 v[22:23], v[24:25], v[22:23] op_sel_hi:[0,1]
	v_pk_mul_f32 v[24:25], v[24:25], v[8:9] op_sel_hi:[0,1]
	v_pk_mul_f32 v[6:7], v[10:11], v[20:21]
	v_pk_mul_f32 v[8:9], v[12:13], v[26:27]
	v_pk_mul_f32 v[10:11], v[14:15], v[22:23]
	v_pk_mul_f32 v[12:13], v[16:17], v[24:25]
	global_store_dwordx4 v[18:19], v[6:9], off nt
	global_store_dwordx4 v[18:19], v[10:13], off offset:16 nt
	s_andn2_b64 exec, exec, s[8:9]
	s_cbranch_execnz .Lp8_loop_prompt
	s_mov_b64 exec, -1
